# Odd layers: convert_p (p f32->bf16) also folded into the S5 chunk loop on waves 5-7 (LDS-DMA landing), separate loop removed
# speedup vs baseline: 1.0640x; 1.0037x over previous
.LBB0_1089:
	s_and_b32 s42, s44, 31
	s_lshl_b32 s42, s42, 5
	s_mov_b32 s43, s3
	v_lshl_add_u64 v[114:115], s[40:41], 0, v[66:67]
	v_mov_b32_e32 v66, v67
	v_lshl_add_u64 v[112:113], v[84:85], 0, s[42:43]
	v_cndmask_b32_e64 v109, v16, v138, s[6:7]
	v_cndmask_b32_e64 v144, v17, v139, s[6:7]
	v_cndmask_b32_e64 v145, v18, v140, s[6:7]
	v_cndmask_b32_e64 v146, v19, v141, s[6:7]
	v_lshl_add_u64 v[116:117], v[82:83], 0, s[36:37]
	v_lshl_add_u64 v[110:111], v[86:87], 0, s[2:3]
	v_lshl_add_u64 v[118:119], v[78:79], 0, s[2:3]
	v_xor_b32_e32 v62, 0x80000000, v63
	v_mov_b32_e32 v61, v60
	v_lshl_add_u64 v[120:121], v[94:95], 0, s[38:39]
	s_mov_b32 s40, 0
	s_movk_i32 s2, 0xffc0
	v_mov_b64_e32 v[122:123], v[66:67]
	s_waitcnt lgkmcnt(0)
	v_lshrrev_b32_e32 v204, 6, v206
	v_and_b32_e32 v205, 63, v206
	v_readfirstlane_b32 s72, v204
	s_load_dwordx2 s[58:59], s[0:1], 0xf0
	s_load_dwordx2 s[70:71], s[0:1], 0xd8
	s_load_dwordx2 s[92:93], s[0:1], 0x8
	v_lshlrev_b32_e32 v204, 5, v205
	v_lshlrev_b32_e32 v205, 4, v205
	s_mov_b32 s54, 0
	s_mov_b32 s55, 0
	s_mov_b32 s85, 0
	s_mov_b32 s90, 102400
	s_cmp_eq_u32 s72, 6
	s_cselect_b32 s90, 116736, s90
	s_cmp_eq_u32 s72, 7
	s_cselect_b32 s90, 133120, s90
	s_waitcnt lgkmcnt(0)
	s_add_u32 s98, s58, 0x7000000
	s_addc_u32 s99, s59, 0
	s_add_u32 s92, s92, 0x2000000
	s_addc_u32 s93, s93, 0
	s_add_u32 s60, s58, 0xc000000
	s_addc_u32 s61, s59, 0
	s_add_u32 s58, s58, 0x10000000
	s_addc_u32 s59, s59, 0
	global_load_dwordx4 v[208:211], v204, s[70:71]
	global_load_dwordx4 v[212:215], v204, s[70:71] offset:16
	s_add_u32 s70, s70, 0x800
	s_addc_u32 s71, s71, 0
	global_load_dwordx4 v[216:219], v204, s[70:71]
	global_load_dwordx4 v[220:223], v204, s[70:71] offset:16
	s_add_u32 s70, s70, 0x800
	s_addc_u32 s71, s71, 0
	global_load_dwordx4 v[224:227], v204, s[70:71]
	global_load_dwordx4 v[228:231], v204, s[70:71] offset:16
	s_waitcnt vmcnt(0)
	s_mov_b32 s71, 0
	v_add_u32_e32 v204, 0x400, v205
	v_add_u32_e32 v252, 0x800, v205
	v_add_u32_e32 v253, 0xc00, v205
	s_barrier
	s_branch .LBB0_1092

.Ls5T_noperm_0:
	s_cmp_eq_u32 s71, 0
	s_cbranch_scc1 .Ls5T_w0_0
	s_cmp_eq_u32 s71, 2
	s_cbranch_scc1 .Ls5T_w4_0
	s_waitcnt vmcnt(7)
	s_branch .Ls5T_mov_0
.Ls5T_w4_0:
	s_waitcnt vmcnt(4)
	s_branch .Ls5T_mov_0

.LBB0_1092:
	s_and_b64 vcc, exec, s[28:29]
	s_cbranch_vccz .LBB0_1107
	s_mov_b32 s100, 0
	s_mov_b32 s71, 0
	s_cmp_lt_u32 s72, 5
	s_cbranch_scc1 .Lcv_topdone_0
	s_cmp_eq_u32 s54, 0
	s_cbranch_scc1 .Lcv_noprev_0
	s_cmp_eq_u32 s54, 2
	s_cbranch_scc1 .Lcv_cp_0
	v_add_u32_e32 v200, s84, v205
	ds_read_b128 v[232:235], v200 offset:0
	ds_read_b128 v[236:239], v200 offset:1024
	ds_read_b128 v[240:243], v200 offset:2048
	ds_read_b128 v[244:247], v200 offset:3072
	ds_read_b128 v[248:251], v200 offset:4096
	ds_read_b128 v[184:187], v200 offset:5120
	ds_read_b128 v[188:191], v200 offset:6144
	s_and_b32 s70, s56, 0xfff
	s_waitcnt lgkmcnt(0)
	v_lshlrev_b32_e32 v200, 16, v232
	v_and_b32_e32 v201, 0xffff0000, v232
	v_lshlrev_b32_e32 v202, 16, v236
	v_and_b32_e32 v203, 0xffff0000, v236
	v_pk_mul_f32 v[200:201], v[208:209], v[200:201]
	v_pk_mul_f32 v[192:193], v[200:201], v[202:203]
	v_lshlrev_b32_e32 v200, 16, v233
	v_and_b32_e32 v201, 0xffff0000, v233
	v_lshlrev_b32_e32 v202, 16, v237
	v_and_b32_e32 v203, 0xffff0000, v237
	v_pk_mul_f32 v[200:201], v[210:211], v[200:201]
	v_pk_mul_f32 v[194:195], v[200:201], v[202:203]
	v_lshlrev_b32_e32 v200, 16, v234
	v_and_b32_e32 v201, 0xffff0000, v234
	v_lshlrev_b32_e32 v202, 16, v238
	v_and_b32_e32 v203, 0xffff0000, v238
	v_pk_mul_f32 v[200:201], v[212:213], v[200:201]
	v_pk_mul_f32 v[196:197], v[200:201], v[202:203]
	v_lshlrev_b32_e32 v200, 16, v235
	v_and_b32_e32 v201, 0xffff0000, v235
	v_lshlrev_b32_e32 v202, 16, v239
	v_and_b32_e32 v203, 0xffff0000, v239
	v_pk_mul_f32 v[200:201], v[214:215], v[200:201]
	v_pk_mul_f32 v[198:199], v[200:201], v[202:203]
	s_cmp_lt_u32 s70, 1
	s_cbranch_scc1 .Lcv_taps_done_0
	v_lshlrev_b32_e32 v200, 16, v240
	v_and_b32_e32 v201, 0xffff0000, v240
	v_lshlrev_b32_e32 v202, 16, v244
	v_and_b32_e32 v203, 0xffff0000, v244
	v_pk_mul_f32 v[200:201], v[216:217], v[200:201]
	v_pk_fma_f32 v[192:193], v[200:201], v[202:203], v[192:193]
	v_lshlrev_b32_e32 v200, 16, v241
	v_and_b32_e32 v201, 0xffff0000, v241
	v_lshlrev_b32_e32 v202, 16, v245
	v_and_b32_e32 v203, 0xffff0000, v245
	v_pk_mul_f32 v[200:201], v[218:219], v[200:201]
	v_pk_fma_f32 v[194:195], v[200:201], v[202:203], v[194:195]
	v_lshlrev_b32_e32 v200, 16, v242
	v_and_b32_e32 v201, 0xffff0000, v242
	v_lshlrev_b32_e32 v202, 16, v246
	v_and_b32_e32 v203, 0xffff0000, v246
	v_pk_mul_f32 v[200:201], v[220:221], v[200:201]
	v_pk_fma_f32 v[196:197], v[200:201], v[202:203], v[196:197]
	v_lshlrev_b32_e32 v200, 16, v243
	v_and_b32_e32 v201, 0xffff0000, v243
	v_lshlrev_b32_e32 v202, 16, v247
	v_and_b32_e32 v203, 0xffff0000, v247
	v_pk_mul_f32 v[200:201], v[222:223], v[200:201]
	v_pk_fma_f32 v[198:199], v[200:201], v[202:203], v[198:199]
	s_cmp_lt_u32 s70, 2
	s_cbranch_scc1 .Lcv_taps_done_0
	v_lshlrev_b32_e32 v200, 16, v248
	v_and_b32_e32 v201, 0xffff0000, v248
	v_lshlrev_b32_e32 v202, 16, v184
	v_and_b32_e32 v203, 0xffff0000, v184
	v_pk_mul_f32 v[200:201], v[224:225], v[200:201]
	v_pk_fma_f32 v[192:193], v[200:201], v[202:203], v[192:193]
	v_lshlrev_b32_e32 v200, 16, v249
	v_and_b32_e32 v201, 0xffff0000, v249
	v_lshlrev_b32_e32 v202, 16, v185
	v_and_b32_e32 v203, 0xffff0000, v185
	v_pk_mul_f32 v[200:201], v[226:227], v[200:201]
	v_pk_fma_f32 v[194:195], v[200:201], v[202:203], v[194:195]
	v_lshlrev_b32_e32 v200, 16, v250
	v_and_b32_e32 v201, 0xffff0000, v250
	v_lshlrev_b32_e32 v202, 16, v186
	v_and_b32_e32 v203, 0xffff0000, v186
	v_pk_mul_f32 v[200:201], v[228:229], v[200:201]
	v_pk_fma_f32 v[196:197], v[200:201], v[202:203], v[196:197]
	v_lshlrev_b32_e32 v200, 16, v251
	v_and_b32_e32 v201, 0xffff0000, v251
	v_lshlrev_b32_e32 v202, 16, v187
	v_and_b32_e32 v203, 0xffff0000, v187
	v_pk_mul_f32 v[200:201], v[230:231], v[200:201]
	v_pk_fma_f32 v[198:199], v[200:201], v[202:203], v[198:199]
.Lcv_taps_done_0:
	v_lshlrev_b32_e32 v200, 16, v188
	v_and_b32_e32 v201, 0xffff0000, v188
	v_pk_mul_f32 v[192:193], v[192:193], v[200:201]
	v_lshlrev_b32_e32 v200, 16, v189
	v_and_b32_e32 v201, 0xffff0000, v189
	v_pk_mul_f32 v[194:195], v[194:195], v[200:201]
	v_lshlrev_b32_e32 v200, 16, v190
	v_and_b32_e32 v201, 0xffff0000, v190
	v_pk_mul_f32 v[196:197], v[196:197], v[200:201]
	v_lshlrev_b32_e32 v200, 16, v191
	v_and_b32_e32 v201, 0xffff0000, v191
	v_pk_mul_f32 v[198:199], v[198:199], v[200:201]
	v_cvt_pk_bf16_f32 v232, v192, v193
	v_cvt_pk_bf16_f32 v233, v194, v195
	v_cvt_pk_bf16_f32 v234, v196, v197
	v_cvt_pk_bf16_f32 v235, v198, v199
	global_store_dwordx4 v205, v[232:235], s[68:69] offset:1024
	s_branch .Lcv_noprev_0
.Lcv_cp_0:
	v_lshlrev_b32_e32 v200, 1, v205
	v_add_u32_e32 v200, s84, v200
	ds_read_b128 v[232:235], v200
	ds_read_b128 v[236:239], v200 offset:16
	ds_read_b128 v[240:243], v200 offset:2048
	ds_read_b128 v[244:247], v200 offset:2064
	s_waitcnt lgkmcnt(0)
	v_cvt_pk_bf16_f32 v248, v232, v233
	v_cvt_pk_bf16_f32 v249, v234, v235
	v_cvt_pk_bf16_f32 v250, v236, v237
	v_cvt_pk_bf16_f32 v251, v238, v239
	v_cvt_pk_bf16_f32 v184, v240, v241
	v_cvt_pk_bf16_f32 v185, v242, v243
	v_cvt_pk_bf16_f32 v186, v244, v245
	v_cvt_pk_bf16_f32 v187, v246, v247
	global_store_dwordx4 v205, v[248:251], s[68:69]
	global_store_dwordx4 v205, v[184:187], s[68:69] offset:1024

.Lcv_noissue_0:
	s_mov_b32 s55, 43
	s_branch .Lcv_done_0
.Lcv_cpissue_0:
	s_cmp_ge_u32 s55, 54
	s_cbranch_scc1 .Lcv_done_0
	s_sub_u32 s57, s55, 43
	s_mul_i32 s57, s57, 0x300
	s_mul_i32 s70, s96, 3
	s_add_u32 s57, s57, s70
	s_add_u32 s57, s57, s72
	s_sub_u32 s57, s57, 5
	s_and_b32 s87, s55, 1
	s_add_u32 s55, s55, 1
	s_cmp_ge_u32 s57, 0x2000
	s_cbranch_scc1 .Lcv_done_0
	s_lshl_b32 s70, s57, 12
	s_add_u32 s62, s92, s70
	s_addc_u32 s63, s93, 0
	s_lshl_b32 s70, s57, 11
	s_add_u32 s88, s98, s70
	s_addc_u32 s89, s99, 0
	s_mul_i32 s70, s87, 0x1c00
	s_add_u32 s87, s90, s70
	s_mov_b32 s70, m0
	s_add_u32 m0, s87, 0
	s_nop 0
	global_load_lds_dwordx4 v205, s[62:63]
	s_add_u32 m0, s87, 1024
	s_nop 0
	global_load_lds_dwordx4 v204, s[62:63]
	s_add_u32 m0, s87, 2048
	s_nop 0
	global_load_lds_dwordx4 v252, s[62:63]
	s_add_u32 m0, s87, 3072
	s_nop 0
	global_load_lds_dwordx4 v253, s[62:63]
	s_mov_b32 m0, s70
	s_mov_b32 s85, 2
	s_mov_b32 s71, 2

.LBB0_1118:
	s_or_b64 exec, exec, s[6:7]
	s_mov_b32 s14, 0
	v_cmp_gt_i32_e32 vcc, s14, v16
	s_and_saveexec_b64 s[6:7], vcc
	s_cbranch_execz .LBB0_1123
	s_load_dwordx2 s[4:5], s[4:5], 0x8
	v_lshlrev_b32_e32 v0, 1, v16
	v_ashrrev_i32_e32 v1, 31, v0
	v_ashrrev_i32_e32 v17, 31, v16
	v_add_lshl_u32 v18, v16, s82, 1
	s_waitcnt lgkmcnt(0)
	s_add_u32 s8, s4, 0x2000000
	s_addc_u32 s9, s5, 0
	v_lshl_add_u64 v[8:9], v[0:1], 4, s[8:9]
	global_load_dwordx4 v[0:3], v[8:9], off offset:16 nt
	global_load_dwordx4 v[4:7], v[8:9], off nt
	s_mov_b64 s[4:5], 0x7000000
	v_lshl_add_u64 v[8:9], v[16:17], 4, s[2:3]
	v_lshl_add_u64 v[20:21], v[8:9], 0, s[4:5]
	s_ashr_i32 s83, s82, 31
	s_mov_b64 s[10:11], 0
	s_mov_b32 s15, 0xfffff
	s_lshl_b32 s16, s33, 10
	s_lshl_b64 s[2:3], s[82:83], 4
	s_waitcnt vmcnt(1)
	v_mov_b64_e32 v[10:11], v[2:3]
	s_waitcnt vmcnt(0)
	v_mov_b64_e32 v[14:15], v[6:7]
	v_mov_b64_e32 v[8:9], v[0:1]
	v_mov_b64_e32 v[12:13], v[4:5]
	s_branch .LBB0_1121

.LBB0_2569:
	s_and_b32 s2, s44, 31
	s_lshl_b32 s2, s2, 5
	v_lshl_add_u64 v[112:113], v[84:85], 0, s[2:3]
	v_lshl_add_u64 v[114:115], s[40:41], 0, v[66:67]
	s_lshl_b32 s2, s53, 1
	v_mov_b32_e32 v66, v67
	v_cndmask_b32_e64 v109, v16, v138, s[6:7]
	v_cndmask_b32_e64 v144, v17, v139, s[6:7]
	v_cndmask_b32_e64 v145, v18, v140, s[6:7]
	v_cndmask_b32_e64 v146, v19, v141, s[6:7]
	v_lshl_add_u64 v[116:117], v[82:83], 0, s[36:37]
	v_lshl_add_u64 v[110:111], v[86:87], 0, s[2:3]
	v_lshl_add_u64 v[118:119], v[78:79], 0, s[2:3]
	v_xor_b32_e32 v62, 0x80000000, v63
	v_mov_b32_e32 v61, v60
	v_lshl_add_u64 v[120:121], v[94:95], 0, s[38:39]
	s_mov_b32 s40, 0
	s_movk_i32 s2, 0xffc0
	v_mov_b64_e32 v[122:123], v[66:67]
	s_waitcnt lgkmcnt(0)
	v_lshrrev_b32_e32 v204, 6, v206
	v_and_b32_e32 v205, 63, v206
	v_readfirstlane_b32 s72, v204
	s_load_dwordx2 s[58:59], s[0:1], 0xf0
	s_load_dwordx2 s[70:71], s[0:1], 0xd8
	s_load_dwordx2 s[92:93], s[0:1], 0x8
	v_lshlrev_b32_e32 v204, 5, v205
	v_lshlrev_b32_e32 v205, 4, v205
	s_mov_b32 s54, 0
	s_mov_b32 s55, 0
	s_mov_b32 s85, 0
	s_mov_b32 s90, 102400
	s_cmp_eq_u32 s72, 6
	s_cselect_b32 s90, 116736, s90
	s_cmp_eq_u32 s72, 7
	s_cselect_b32 s90, 133120, s90
	s_waitcnt lgkmcnt(0)
	s_add_u32 s98, s58, 0x7000000
	s_addc_u32 s99, s59, 0
	s_add_u32 s92, s92, 0x6000000
	s_addc_u32 s93, s93, 0
	s_add_u32 s60, s58, 0xc000000
	s_addc_u32 s61, s59, 0
	s_add_u32 s58, s58, 0x10000000
	s_addc_u32 s59, s59, 0
	s_add_u32 s70, s70, 0x1800
	s_addc_u32 s71, s71, 0
	global_load_dwordx4 v[208:211], v204, s[70:71]
	global_load_dwordx4 v[212:215], v204, s[70:71] offset:16
	s_add_u32 s70, s70, 0x800
	s_addc_u32 s71, s71, 0
	global_load_dwordx4 v[216:219], v204, s[70:71]
	global_load_dwordx4 v[220:223], v204, s[70:71] offset:16
	s_add_u32 s70, s70, 0x800
	s_addc_u32 s71, s71, 0
	global_load_dwordx4 v[224:227], v204, s[70:71]
	global_load_dwordx4 v[228:231], v204, s[70:71] offset:16
	s_waitcnt vmcnt(0)
	s_mov_b32 s71, 0
	v_add_u32_e32 v204, 0x400, v205
	v_add_u32_e32 v252, 0x800, v205
	v_add_u32_e32 v253, 0xc00, v205
	s_barrier
	s_branch .LBB0_2572

.Lcv_cpissue_1:
	s_cmp_ge_u32 s55, 54
	s_cbranch_scc1 .Lcv_done_1
	s_sub_u32 s57, s55, 43
	s_mul_i32 s57, s57, 0x300
	s_mul_i32 s70, s95, 3
	s_add_u32 s57, s57, s70
	s_add_u32 s57, s57, s72
	s_sub_u32 s57, s57, 5
	s_and_b32 s87, s55, 1
	s_add_u32 s55, s55, 1
	s_cmp_ge_u32 s57, 0x2000
	s_cbranch_scc1 .Lcv_done_1
	s_lshl_b32 s70, s57, 12
	s_add_u32 s62, s92, s70
	s_addc_u32 s63, s93, 0
	s_lshl_b32 s70, s57, 11
	s_add_u32 s88, s98, s70
	s_addc_u32 s89, s99, 0
	s_mul_i32 s70, s87, 0x1c00
	s_add_u32 s87, s90, s70
	s_mov_b32 s70, m0
	s_add_u32 m0, s87, 0
	s_nop 0
	global_load_lds_dwordx4 v205, s[62:63]
	s_add_u32 m0, s87, 1024
	s_nop 0
	global_load_lds_dwordx4 v204, s[62:63]
	s_add_u32 m0, s87, 2048
	s_nop 0
	global_load_lds_dwordx4 v252, s[62:63]
	s_add_u32 m0, s87, 3072
	s_nop 0
	global_load_lds_dwordx4 v253, s[62:63]
	s_mov_b32 m0, s70
	s_mov_b32 s85, 2
	s_mov_b32 s71, 2

.LBB0_2598:
	s_or_b64 exec, exec, s[6:7]
	s_mov_b32 s14, 0
	v_cmp_gt_i32_e32 vcc, s14, v16
	s_and_saveexec_b64 s[6:7], vcc
	s_cbranch_execz .LBB0_2603
	s_load_dwordx2 s[4:5], s[4:5], 0x8
	v_lshlrev_b32_e32 v0, 1, v16
	v_ashrrev_i32_e32 v1, 31, v0
	v_ashrrev_i32_e32 v17, 31, v16
	v_add_lshl_u32 v18, v16, s82, 1
	s_waitcnt lgkmcnt(0)
	s_add_u32 s8, s4, 0x6000000
	s_addc_u32 s9, s5, 0
	v_lshl_add_u64 v[8:9], v[0:1], 4, s[8:9]
	global_load_dwordx4 v[0:3], v[8:9], off offset:16 nt
	global_load_dwordx4 v[4:7], v[8:9], off nt
	s_mov_b64 s[4:5], 0x7000000
	v_lshl_add_u64 v[8:9], v[16:17], 4, s[2:3]
	v_lshl_add_u64 v[20:21], v[8:9], 0, s[4:5]
	s_ashr_i32 s83, s82, 31
	s_mov_b64 s[10:11], 0
	s_mov_b32 s15, 0xfffff
	s_lshl_b32 s16, s33, 10
	s_lshl_b64 s[2:3], s[82:83], 4
	s_waitcnt vmcnt(1)
	v_mov_b64_e32 v[10:11], v[2:3]
	s_waitcnt vmcnt(0)
	v_mov_b64_e32 v[14:15], v[6:7]
	v_mov_b64_e32 v[8:9], v[0:1]
	v_mov_b64_e32 v[12:13], v[4:5]
	s_branch .LBB0_2601
